# v84 + SSD chunk loop: 6 dead per-chunk readlane reloads (s60-s65) removed
# baseline (speedup 1.0000x reference)
; __device__ __forceinline__ unsigned pk2(float lo, float hi) { unsigned r; asm("v_cvt_pk_bf16_f32 %0, %1, %2" : "=v"(r) : "v"(lo), "v"(hi)); return r; }
; __device__ __forceinline__ float silu_f(float v) { return v * __builtin_amdgcn_rcpf(1.f + __expf(-v)); }
; __device__ __forceinline__ void conv_rows(const u32x4 (&rawp)[5], const float* wl, float (&o0)[8], float (&o1)[8]) {
;     float raw[5][8];
; #pragma unroll
;     for (int q = 0; q < 5; ++q) unpack8(rawp[q], raw[q]);
; #pragma unroll
;     for (int h = 0; h < 2; ++h) {
;         const f32x4 bv = *(const f32x4*)(wl + 4 * 128 + h * 4);
;         f32x4 a0 = bv, a1 = bv;
; #pragma unroll
;         for (int k = 0; k < 4; ++k) { const f32x4 wv = *(const f32x4*)(wl + k * 128 + h * 4);
; #pragma unroll
;             for (int i = 0; i < 4; ++i) { a0[i] += wv[i] * raw[k][h * 4 + i]; a1[i] += wv[i] * raw[k + 1][h * 4 + i]; } }
; #pragma unroll
;         for (int i = 0; i < 4; ++i) { o0[h * 4 + i] = silu_f(a0[i]); o1[h * 4 + i] = silu_f(a1[i]); }
;         __builtin_amdgcn_sched_barrier(0);
;     }
; }
; __device__ __forceinline__ void phase_ssd(const Params& p, uchar* sm, int j, bf16_t* zx, const float* dtraw, float* ssqb) {
;     ...
;             conv_rows(rx, wlx, xo0, xo1);
;             __builtin_amdgcn_sched_barrier(0);
; #pragma unroll
;             for (int i = 0; i < 8; ++i) *(unsigned*)(sm + L_XT + (c8 * 8 + i) * RS_T + ((lp ^ swz) * 4)) = pk2(xo0[i], xo1[i]);
.LBB0_466:
	ds_read_b128 v[132:135], v187 offset:2048
	ds_read_b128 v[96:99], v187 offset:0
	ds_read_b128 v[120:123], v187 offset:512
	ds_read_b128 v[124:127], v187 offset:1024
	ds_read_b128 v[128:131], v187 offset:1536
	s_nop 0
	v_lshlrev_b32_e32 v100, 16, v4
	v_and_b32_e32 v101, 0xffff0000, v4
	v_lshlrev_b32_e32 v118, 16, v5
	v_and_b32_e32 v119, 0xffff0000, v5
	s_waitcnt lgkmcnt(3)
	v_pk_fma_f32 v[144:145], v[96:97], v[100:101], v[132:133]
	v_pk_fma_f32 v[178:179], v[98:99], v[118:119], v[134:135]
	v_lshlrev_b32_e32 v100, 16, v8
	v_and_b32_e32 v101, 0xffff0000, v8
	v_lshlrev_b32_e32 v118, 16, v9
	v_and_b32_e32 v119, 0xffff0000, v9
	s_waitcnt lgkmcnt(2)
	v_pk_fma_f32 v[144:145], v[120:121], v[100:101], v[144:145]
	v_pk_fma_f32 v[178:179], v[122:123], v[118:119], v[178:179]
	v_pk_fma_f32 v[180:181], v[96:97], v[100:101], v[132:133]
	v_pk_fma_f32 v[230:231], v[98:99], v[118:119], v[134:135]
	v_lshlrev_b32_e32 v100, 16, v12
	v_and_b32_e32 v101, 0xffff0000, v12
	v_lshlrev_b32_e32 v118, 16, v13
	v_and_b32_e32 v119, 0xffff0000, v13
	s_waitcnt lgkmcnt(1)
	v_pk_fma_f32 v[144:145], v[124:125], v[100:101], v[144:145]
	v_pk_fma_f32 v[178:179], v[126:127], v[118:119], v[178:179]
	v_pk_fma_f32 v[180:181], v[120:121], v[100:101], v[180:181]
	v_pk_fma_f32 v[230:231], v[122:123], v[118:119], v[230:231]
	v_lshlrev_b32_e32 v100, 16, v16
	v_and_b32_e32 v101, 0xffff0000, v16
	v_lshlrev_b32_e32 v118, 16, v17
	v_and_b32_e32 v119, 0xffff0000, v17
	s_waitcnt lgkmcnt(0)
	v_pk_fma_f32 v[144:145], v[128:129], v[100:101], v[144:145]
	v_pk_fma_f32 v[178:179], v[130:131], v[118:119], v[178:179]
	v_pk_fma_f32 v[180:181], v[124:125], v[100:101], v[180:181]
	v_pk_fma_f32 v[230:231], v[126:127], v[118:119], v[230:231]
	v_lshlrev_b32_e32 v100, 16, v24
	v_and_b32_e32 v101, 0xffff0000, v24
	v_lshlrev_b32_e32 v118, 16, v25
	v_and_b32_e32 v119, 0xffff0000, v25
	v_pk_fma_f32 v[180:181], v[128:129], v[100:101], v[180:181]
	v_pk_fma_f32 v[230:231], v[130:131], v[118:119], v[230:231]
	v_pk_mul_f32 v[96:97], v[144:145], s[98:99]
	v_pk_mul_f32 v[98:99], v[178:179], s[98:99]
	v_pk_mul_f32 v[120:121], v[180:181], s[98:99]
	v_pk_mul_f32 v[122:123], v[230:231], s[98:99]
	v_exp_f32_e32 v96, v96
	v_exp_f32_e32 v97, v97
	v_exp_f32_e32 v98, v98
	v_exp_f32_e32 v99, v99
	v_exp_f32_e32 v120, v120
	v_exp_f32_e32 v121, v121
	v_exp_f32_e32 v122, v122
	v_exp_f32_e32 v123, v123
	v_pk_add_f32 v[96:97], v[96:97], s[100:101]
	v_pk_add_f32 v[98:99], v[98:99], s[100:101]
	v_pk_add_f32 v[120:121], v[120:121], s[100:101]
	v_pk_add_f32 v[122:123], v[122:123], s[100:101]
	ds_read_b128 v[132:135], v187 offset:2064
	ds_read_b128 v[112:115], v187 offset:16
	v_rcp_f32_e32 v96, v96
	v_rcp_f32_e32 v97, v97
	v_rcp_f32_e32 v98, v98
	ds_read_b128 v[232:235], v187 offset:528
	v_rcp_f32_e32 v99, v99
	v_rcp_f32_e32 v120, v120
	v_rcp_f32_e32 v121, v121
	v_rcp_f32_e32 v122, v122
	ds_read_b128 v[124:127], v187 offset:1040
	v_rcp_f32_e32 v123, v123
	v_pk_mul_f32 v[104:105], v[144:145], v[96:97]
	v_pk_mul_f32 v[106:107], v[178:179], v[98:99]
	v_pk_mul_f32 v[102:103], v[180:181], v[120:121]
	ds_read_b128 v[128:131], v187 offset:1552
	v_pk_mul_f32 v[108:109], v[230:231], v[122:123]
	v_lshlrev_b32_e32 v100, 16, v6
	v_and_b32_e32 v101, 0xffff0000, v6
	v_lshlrev_b32_e32 v118, 16, v7
	v_and_b32_e32 v119, 0xffff0000, v7
	s_waitcnt lgkmcnt(3)
	v_pk_fma_f32 v[144:145], v[112:113], v[100:101], v[132:133]
	v_pk_fma_f32 v[178:179], v[114:115], v[118:119], v[134:135]
	v_lshlrev_b32_e32 v100, 16, v10
	v_and_b32_e32 v101, 0xffff0000, v10
	v_lshlrev_b32_e32 v118, 16, v11
	v_and_b32_e32 v119, 0xffff0000, v11
	s_waitcnt lgkmcnt(2)
	v_pk_fma_f32 v[144:145], v[232:233], v[100:101], v[144:145]
	v_pk_fma_f32 v[178:179], v[234:235], v[118:119], v[178:179]
	v_pk_fma_f32 v[180:181], v[112:113], v[100:101], v[132:133]
	v_pk_fma_f32 v[230:231], v[114:115], v[118:119], v[134:135]
	v_lshlrev_b32_e32 v100, 16, v14
	v_and_b32_e32 v101, 0xffff0000, v14
	v_lshlrev_b32_e32 v118, 16, v15
	v_and_b32_e32 v119, 0xffff0000, v15
	s_waitcnt lgkmcnt(1)
	v_pk_fma_f32 v[144:145], v[124:125], v[100:101], v[144:145]
	v_pk_fma_f32 v[178:179], v[126:127], v[118:119], v[178:179]
	v_pk_fma_f32 v[180:181], v[232:233], v[100:101], v[180:181]
	v_pk_fma_f32 v[230:231], v[234:235], v[118:119], v[230:231]
	v_lshlrev_b32_e32 v100, 16, v18
	v_and_b32_e32 v101, 0xffff0000, v18
	v_lshlrev_b32_e32 v118, 16, v19
	v_and_b32_e32 v119, 0xffff0000, v19
	s_waitcnt lgkmcnt(0)
	v_pk_fma_f32 v[144:145], v[128:129], v[100:101], v[144:145]
	v_pk_fma_f32 v[178:179], v[130:131], v[118:119], v[178:179]
	v_pk_fma_f32 v[180:181], v[124:125], v[100:101], v[180:181]
	v_pk_fma_f32 v[230:231], v[126:127], v[118:119], v[230:231]
	v_lshlrev_b32_e32 v100, 16, v26
	v_and_b32_e32 v101, 0xffff0000, v26
	v_lshlrev_b32_e32 v118, 16, v27
	v_and_b32_e32 v119, 0xffff0000, v27
	v_pk_fma_f32 v[180:181], v[128:129], v[100:101], v[180:181]
	v_pk_fma_f32 v[230:231], v[130:131], v[118:119], v[230:231]
	v_pk_mul_f32 v[96:97], v[144:145], s[98:99]
	v_pk_mul_f32 v[98:99], v[178:179], s[98:99]
	v_pk_mul_f32 v[120:121], v[180:181], s[98:99]
	v_pk_mul_f32 v[122:123], v[230:231], s[98:99]
	v_exp_f32_e32 v96, v96
	v_exp_f32_e32 v97, v97
	v_exp_f32_e32 v98, v98
	v_exp_f32_e32 v99, v99
	v_exp_f32_e32 v120, v120
	v_exp_f32_e32 v121, v121
	v_exp_f32_e32 v122, v122
	v_exp_f32_e32 v123, v123
	v_pk_add_f32 v[96:97], v[96:97], s[100:101]
	v_pk_add_f32 v[98:99], v[98:99], s[100:101]
	v_pk_add_f32 v[120:121], v[120:121], s[100:101]
	v_pk_add_f32 v[122:123], v[122:123], s[100:101]
	v_rcp_f32_e32 v96, v96
	v_rcp_f32_e32 v97, v97
	v_rcp_f32_e32 v98, v98
	v_rcp_f32_e32 v99, v99
	v_rcp_f32_e32 v120, v120
	v_rcp_f32_e32 v121, v121
	v_rcp_f32_e32 v122, v122
	v_rcp_f32_e32 v123, v123
	v_pk_mul_f32 v[110:111], v[144:145], v[96:97]
	v_pk_mul_f32 v[112:113], v[178:179], v[98:99]
	v_pk_mul_f32 v[114:115], v[180:181], v[120:121]
	v_pk_mul_f32 v[116:117], v[230:231], v[122:123]
	v_cvt_pk_bf16_f32 v96, v104, v102
	v_cvt_pk_bf16_f32 v97, v105, v103
	v_add_u32_e32 v98, 0xd000, v206
	ds_write2_b32 v98, v96, v97 offset1:36
	v_cvt_pk_bf16_f32 v96, v106, v108
	v_cvt_pk_bf16_f32 v97, v107, v109
	ds_write2_b32 v98, v96, v97 offset0:72 offset1:108
	v_cvt_pk_bf16_f32 v96, v110, v114
	v_cvt_pk_bf16_f32 v97, v111, v115
	ds_write2_b32 v98, v96, v97 offset0:144 offset1:180
	v_cvt_pk_bf16_f32 v96, v112, v116
	v_cvt_pk_bf16_f32 v97, v113, v117
	ds_write2_b32 v98, v96, v97 offset0:216 offset1:252
	ds_read_b128 v[232:235], v187 offset:4608
	ds_read_b128 v[96:99], v187 offset:2560
	ds_read_b128 v[124:127], v187 offset:3072
	ds_read_b128 v[128:131], v187 offset:3584
	ds_read_b128 v[132:135], v187 offset:4096
	s_waitcnt vmcnt(2)
; __device__ __forceinline__ unsigned pk2(float lo, float hi) { unsigned r; asm("v_cvt_pk_bf16_f32 %0, %1, %2" : "=v"(r) : "v"(lo), "v"(hi)); return r; }
; __device__ __forceinline__ u32x4 pack8(const float (&o)[8]) { u32x4 r; r.x = pk2(o[0], o[1]); r.y = pk2(o[2], o[3]); r.z = pk2(o[4], o[5]); r.w = pk2(o[6], o[7]); return r; }
; __device__ __forceinline__ float silu_f(float v) { return v * __builtin_amdgcn_rcpf(1.f + __expf(-v)); }
; __device__ __forceinline__ void conv_rows(const u32x4 (&rawp)[5], const float* wl, float (&o0)[8], float (&o1)[8]) {
;     float raw[5][8];
; #pragma unroll
;     for (int q = 0; q < 5; ++q) unpack8(rawp[q], raw[q]);
; #pragma unroll
;     for (int h = 0; h < 2; ++h) {
;         const f32x4 bv = *(const f32x4*)(wl + 4 * 128 + h * 4);
;         f32x4 a0 = bv, a1 = bv;
; #pragma unroll
;         for (int k = 0; k < 4; ++k) { const f32x4 wv = *(const f32x4*)(wl + k * 128 + h * 4);
; #pragma unroll
;             for (int i = 0; i < 4; ++i) { a0[i] += wv[i] * raw[k][h * 4 + i]; a1[i] += wv[i] * raw[k + 1][h * 4 + i]; } }
; #pragma unroll
;         for (int i = 0; i < 4; ++i) { o0[h * 4 + i] = silu_f(a0[i]); o1[h * 4 + i] = silu_f(a1[i]); }
;         __builtin_amdgcn_sched_barrier(0);
;     }
; }
; __device__ __forceinline__ void phase_ssd(const Params& p, uchar* sm, int j, bf16_t* zx, const float* dtraw, float* ssqb) {
;     ...
;                 conv_rows(rb, wlb, t0, t1);
;                 __builtin_amdgcn_sched_barrier(0);
;                 *(u32x4*)(sm + L_B + (2 * lp) * RS_CB + c8 * 16) = pack8(t0);
;                 *(u32x4*)(sm + L_B + (2 * lp + 1) * RS_CB + c8 * 16) = pack8(t1);
; #pragma unroll
;                 for (int i = 0; i < 8; ++i) *(unsigned*)(sm + L_BT + (c8 * 8 + i) * RS_T + ((lp ^ swz) * 4)) = pk2(t0[i], t1[i]);
	v_lshlrev_b32_e32 v144, 16, v20
	v_and_b32_e32 v145, 0xffff0000, v20
	v_lshlrev_b32_e32 v178, 16, v21
	v_and_b32_e32 v179, 0xffff0000, v21
	s_waitcnt lgkmcnt(3)
	v_pk_fma_f32 v[180:181], v[96:97], v[144:145], v[232:233]
	v_pk_fma_f32 v[230:231], v[98:99], v[178:179], v[234:235]
	v_lshlrev_b32_e32 v144, 16, v28
	v_and_b32_e32 v145, 0xffff0000, v28
	v_lshlrev_b32_e32 v178, 16, v29
	v_and_b32_e32 v179, 0xffff0000, v29
	s_waitcnt lgkmcnt(2)
	v_pk_fma_f32 v[180:181], v[124:125], v[144:145], v[180:181]
	v_pk_fma_f32 v[230:231], v[126:127], v[178:179], v[230:231]
	v_pk_fma_f32 v[236:237], v[96:97], v[144:145], v[232:233]
	v_pk_fma_f32 v[238:239], v[98:99], v[178:179], v[234:235]
	v_lshlrev_b32_e32 v144, 16, v32
	v_and_b32_e32 v145, 0xffff0000, v32
	v_lshlrev_b32_e32 v178, 16, v33
	v_and_b32_e32 v179, 0xffff0000, v33
	s_waitcnt lgkmcnt(1)
	v_pk_fma_f32 v[180:181], v[128:129], v[144:145], v[180:181]
	v_pk_fma_f32 v[230:231], v[130:131], v[178:179], v[230:231]
	v_pk_fma_f32 v[236:237], v[124:125], v[144:145], v[236:237]
	v_pk_fma_f32 v[238:239], v[126:127], v[178:179], v[238:239]
	v_lshlrev_b32_e32 v144, 16, v36
	v_and_b32_e32 v145, 0xffff0000, v36
	v_lshlrev_b32_e32 v178, 16, v37
	v_and_b32_e32 v179, 0xffff0000, v37
	s_waitcnt lgkmcnt(0)
	v_pk_fma_f32 v[180:181], v[132:133], v[144:145], v[180:181]
	v_pk_fma_f32 v[230:231], v[134:135], v[178:179], v[230:231]
	v_pk_fma_f32 v[236:237], v[128:129], v[144:145], v[236:237]
	v_pk_fma_f32 v[238:239], v[130:131], v[178:179], v[238:239]
	v_lshlrev_b32_e32 v144, 16, v40
	v_and_b32_e32 v145, 0xffff0000, v40
	v_lshlrev_b32_e32 v178, 16, v41
	v_and_b32_e32 v179, 0xffff0000, v41
	v_pk_fma_f32 v[236:237], v[132:133], v[144:145], v[236:237]
	v_pk_fma_f32 v[238:239], v[134:135], v[178:179], v[238:239]
	v_pk_mul_f32 v[96:97], v[180:181], s[98:99]
	v_pk_mul_f32 v[98:99], v[230:231], s[98:99]
	v_pk_mul_f32 v[124:125], v[236:237], s[98:99]
	v_pk_mul_f32 v[126:127], v[238:239], s[98:99]
	v_exp_f32_e32 v96, v96
	v_exp_f32_e32 v97, v97
	v_exp_f32_e32 v98, v98
	v_exp_f32_e32 v99, v99
	v_exp_f32_e32 v124, v124
	v_exp_f32_e32 v125, v125
	v_exp_f32_e32 v126, v126
	v_exp_f32_e32 v127, v127
	v_pk_add_f32 v[96:97], v[96:97], s[100:101]
	v_pk_add_f32 v[98:99], v[98:99], s[100:101]
	v_pk_add_f32 v[124:125], v[124:125], s[100:101]
	v_pk_add_f32 v[126:127], v[126:127], s[100:101]
	ds_read_b128 v[232:235], v187 offset:4624
	ds_read_b128 v[120:123], v187 offset:2576
	v_rcp_f32_e32 v96, v96
	v_rcp_f32_e32 v97, v97
	v_rcp_f32_e32 v98, v98
	ds_read_b128 v[248:251], v187 offset:3088
	v_rcp_f32_e32 v99, v99
	v_rcp_f32_e32 v124, v124
	v_rcp_f32_e32 v125, v125
	v_rcp_f32_e32 v126, v126
	ds_read_b128 v[128:131], v187 offset:3600
	v_rcp_f32_e32 v127, v127
	v_pk_mul_f32 v[240:241], v[180:181], v[96:97]
	v_pk_mul_f32 v[246:247], v[230:231], v[98:99]
	v_pk_mul_f32 v[242:243], v[236:237], v[124:125]
	ds_read_b128 v[132:135], v187 offset:4112
	v_pk_mul_f32 v[252:253], v[238:239], v[126:127]
	v_lshlrev_b32_e32 v144, 16, v22
	v_and_b32_e32 v145, 0xffff0000, v22
	v_lshlrev_b32_e32 v178, 16, v23
	v_and_b32_e32 v179, 0xffff0000, v23
	s_waitcnt lgkmcnt(3)
	v_pk_fma_f32 v[180:181], v[120:121], v[144:145], v[232:233]
	v_pk_fma_f32 v[230:231], v[122:123], v[178:179], v[234:235]
	v_lshlrev_b32_e32 v144, 16, v30
	v_and_b32_e32 v145, 0xffff0000, v30
	v_lshlrev_b32_e32 v178, 16, v31
	v_and_b32_e32 v179, 0xffff0000, v31
	s_waitcnt lgkmcnt(2)
	v_pk_fma_f32 v[180:181], v[248:249], v[144:145], v[180:181]
	v_pk_fma_f32 v[230:231], v[250:251], v[178:179], v[230:231]
	v_pk_fma_f32 v[236:237], v[120:121], v[144:145], v[232:233]
	v_pk_fma_f32 v[238:239], v[122:123], v[178:179], v[234:235]
	v_lshlrev_b32_e32 v144, 16, v34
	v_and_b32_e32 v145, 0xffff0000, v34
	v_lshlrev_b32_e32 v178, 16, v35
	v_and_b32_e32 v179, 0xffff0000, v35
	s_waitcnt lgkmcnt(1)
	v_pk_fma_f32 v[180:181], v[128:129], v[144:145], v[180:181]
	v_pk_fma_f32 v[230:231], v[130:131], v[178:179], v[230:231]
	v_pk_fma_f32 v[236:237], v[248:249], v[144:145], v[236:237]
	v_pk_fma_f32 v[238:239], v[250:251], v[178:179], v[238:239]
	v_lshlrev_b32_e32 v144, 16, v38
	v_and_b32_e32 v145, 0xffff0000, v38
	v_lshlrev_b32_e32 v178, 16, v39
	v_and_b32_e32 v179, 0xffff0000, v39
	s_waitcnt lgkmcnt(0)
	v_pk_fma_f32 v[180:181], v[132:133], v[144:145], v[180:181]
	v_pk_fma_f32 v[230:231], v[134:135], v[178:179], v[230:231]
	v_pk_fma_f32 v[236:237], v[128:129], v[144:145], v[236:237]
	v_pk_fma_f32 v[238:239], v[130:131], v[178:179], v[238:239]
	v_lshlrev_b32_e32 v144, 16, v42
	v_and_b32_e32 v145, 0xffff0000, v42
	v_lshlrev_b32_e32 v178, 16, v43
	v_and_b32_e32 v179, 0xffff0000, v43
	v_pk_fma_f32 v[236:237], v[132:133], v[144:145], v[236:237]
	v_pk_fma_f32 v[238:239], v[134:135], v[178:179], v[238:239]
	v_pk_mul_f32 v[96:97], v[180:181], s[98:99]
	v_pk_mul_f32 v[98:99], v[230:231], s[98:99]
	v_pk_mul_f32 v[124:125], v[236:237], s[98:99]
	v_pk_mul_f32 v[126:127], v[238:239], s[98:99]
	v_exp_f32_e32 v96, v96
	v_exp_f32_e32 v97, v97
	v_exp_f32_e32 v98, v98
	v_exp_f32_e32 v99, v99
	v_exp_f32_e32 v124, v124
	v_exp_f32_e32 v125, v125
	v_exp_f32_e32 v126, v126
	v_exp_f32_e32 v127, v127
	v_pk_add_f32 v[96:97], v[96:97], s[100:101]
	v_pk_add_f32 v[98:99], v[98:99], s[100:101]
	v_pk_add_f32 v[124:125], v[124:125], s[100:101]
	v_pk_add_f32 v[126:127], v[126:127], s[100:101]
	v_rcp_f32_e32 v96, v96
	v_rcp_f32_e32 v97, v97
	v_rcp_f32_e32 v98, v98
	v_rcp_f32_e32 v99, v99
	v_rcp_f32_e32 v124, v124
	v_rcp_f32_e32 v125, v125
	v_rcp_f32_e32 v126, v126
	v_rcp_f32_e32 v127, v127
	v_pk_mul_f32 v[120:121], v[180:181], v[96:97]
	v_pk_mul_f32 v[118:119], v[230:231], v[98:99]
	v_pk_mul_f32 v[122:123], v[236:237], v[124:125]
	v_pk_mul_f32 v[100:101], v[238:239], v[126:127]
	v_cvt_pk_bf16_f32 v96, v240, v241
	v_cvt_pk_bf16_f32 v97, v246, v247
	v_cvt_pk_bf16_f32 v98, v120, v121
	v_cvt_pk_bf16_f32 v99, v118, v119
	ds_write_b128 v207, v[96:99] offset:17408
	v_cvt_pk_bf16_f32 v96, v242, v243
	v_cvt_pk_bf16_f32 v97, v252, v253
	v_cvt_pk_bf16_f32 v98, v122, v123
	v_cvt_pk_bf16_f32 v99, v100, v101
	ds_write_b128 v208, v[96:99] offset:17408
	v_cvt_pk_bf16_f32 v96, v240, v242
	v_cvt_pk_bf16_f32 v97, v241, v243
	v_add_u32_e32 v98, 0x8800, v206
	ds_write2_b32 v98, v96, v97 offset1:36
	v_cvt_pk_bf16_f32 v96, v246, v252
	v_cvt_pk_bf16_f32 v97, v247, v253
	ds_write2_b32 v98, v96, v97 offset0:72 offset1:108
	v_cvt_pk_bf16_f32 v96, v120, v122
	v_cvt_pk_bf16_f32 v97, v121, v123
	ds_write2_b32 v98, v96, v97 offset0:144 offset1:180
	v_cvt_pk_bf16_f32 v96, v118, v100
	v_cvt_pk_bf16_f32 v97, v119, v101
	ds_write2_b32 v98, v96, v97 offset0:216 offset1:252
	ds_read_b128 v[236:239], v187 offset:7168
	ds_read_b128 v[124:127], v187 offset:5120
	ds_read_b128 v[128:131], v187 offset:5632
	ds_read_b128 v[132:135], v187 offset:6144
	ds_read_b128 v[232:235], v187 offset:6656
	v_lshlrev_b32_e32 v96, 16, v44
	v_and_b32_e32 v97, 0xffff0000, v44
	v_lshlrev_b32_e32 v144, 16, v45
	v_and_b32_e32 v145, 0xffff0000, v45
	s_waitcnt lgkmcnt(3)
; __device__ __forceinline__ u32x4 pack8(const float (&o)[8]) { u32x4 r; r.x = pk2(o[0], o[1]); r.y = pk2(o[2], o[3]); r.z = pk2(o[4], o[5]); r.w = pk2(o[6], o[7]); return r; }
; __device__ __forceinline__ float silu_f(float v) { return v * __builtin_amdgcn_rcpf(1.f + __expf(-v)); }
; __device__ __forceinline__ void conv_rows(const u32x4 (&rawp)[5], const float* wl, float (&o0)[8], float (&o1)[8]) {
;     float raw[5][8];
; #pragma unroll
;     for (int q = 0; q < 5; ++q) unpack8(rawp[q], raw[q]);
; #pragma unroll
;     for (int h = 0; h < 2; ++h) {
;         const f32x4 bv = *(const f32x4*)(wl + 4 * 128 + h * 4);
;         f32x4 a0 = bv, a1 = bv;
; #pragma unroll
;         for (int k = 0; k < 4; ++k) { const f32x4 wv = *(const f32x4*)(wl + k * 128 + h * 4);
; #pragma unroll
;             for (int i = 0; i < 4; ++i) { a0[i] += wv[i] * raw[k][h * 4 + i]; a1[i] += wv[i] * raw[k + 1][h * 4 + i]; } }
; #pragma unroll
;         for (int i = 0; i < 4; ++i) { o0[h * 4 + i] = silu_f(a0[i]); o1[h * 4 + i] = silu_f(a1[i]); }
;         __builtin_amdgcn_sched_barrier(0);
;     }
; }
; __device__ __forceinline__ void phase_ssd(const Params& p, uchar* sm, int j, bf16_t* zx, const float* dtraw, float* ssqb) {
;     ...
;                 conv_rows(rc, wlc, t0, t1);
;                 __builtin_amdgcn_sched_barrier(0);
;                 *(u32x4*)(sm + L_C + (2 * lp) * RS_CB + c8 * 16) = pack8(t0);
;                 *(u32x4*)(sm + L_C + (2 * lp + 1) * RS_CB + c8 * 16) = pack8(t1);
;             }
;             const u32x4 xp0 = pack8(xo0), xp1 = pack8(xo1);
;             bf16_t* zc = zx + (size_t)zrow0 * LDZ;
;             if (c + 1 < 32) { const bf16_t* zb = zc + 64 * LDZ;
;                 load_raw(zb + 2048 + colx, toff, false, 2 * lp, rx); }
	v_pk_fma_f32 v[178:179], v[124:125], v[96:97], v[236:237]
	v_pk_fma_f32 v[180:181], v[126:127], v[144:145], v[238:239]
	v_lshlrev_b32_e32 v96, 16, v48
	v_and_b32_e32 v97, 0xffff0000, v48
	v_lshlrev_b32_e32 v144, 16, v49
	v_and_b32_e32 v145, 0xffff0000, v49
	s_waitcnt lgkmcnt(2)
	v_pk_fma_f32 v[178:179], v[128:129], v[96:97], v[178:179]
	v_pk_fma_f32 v[180:181], v[130:131], v[144:145], v[180:181]
	v_pk_fma_f32 v[230:231], v[124:125], v[96:97], v[236:237]
	v_pk_fma_f32 v[246:247], v[126:127], v[144:145], v[238:239]
	v_lshlrev_b32_e32 v96, 16, v52
	v_and_b32_e32 v97, 0xffff0000, v52
	v_lshlrev_b32_e32 v144, 16, v53
	v_and_b32_e32 v145, 0xffff0000, v53
	s_waitcnt lgkmcnt(1)
	v_pk_fma_f32 v[178:179], v[132:133], v[96:97], v[178:179]
	v_pk_fma_f32 v[180:181], v[134:135], v[144:145], v[180:181]
	v_pk_fma_f32 v[230:231], v[128:129], v[96:97], v[230:231]
	v_pk_fma_f32 v[246:247], v[130:131], v[144:145], v[246:247]
	v_lshlrev_b32_e32 v96, 16, v56
	v_and_b32_e32 v97, 0xffff0000, v56
	v_lshlrev_b32_e32 v144, 16, v57
	v_and_b32_e32 v145, 0xffff0000, v57
	s_waitcnt lgkmcnt(0)
	v_pk_fma_f32 v[178:179], v[232:233], v[96:97], v[178:179]
	v_pk_fma_f32 v[180:181], v[234:235], v[144:145], v[180:181]
	v_pk_fma_f32 v[230:231], v[132:133], v[96:97], v[230:231]
	v_pk_fma_f32 v[246:247], v[134:135], v[144:145], v[246:247]
	v_lshlrev_b32_e32 v96, 16, v60
	v_and_b32_e32 v97, 0xffff0000, v60
	v_lshlrev_b32_e32 v144, 16, v61
	v_and_b32_e32 v145, 0xffff0000, v61
	v_pk_fma_f32 v[230:231], v[232:233], v[96:97], v[230:231]
	v_pk_fma_f32 v[246:247], v[234:235], v[144:145], v[246:247]
	v_pk_mul_f32 v[124:125], v[178:179], s[98:99]
	v_pk_mul_f32 v[126:127], v[180:181], s[98:99]
	v_pk_mul_f32 v[128:129], v[230:231], s[98:99]
	v_pk_mul_f32 v[130:131], v[246:247], s[98:99]
	v_exp_f32_e32 v124, v124
	v_exp_f32_e32 v125, v125
	v_exp_f32_e32 v126, v126
	v_exp_f32_e32 v127, v127
	v_exp_f32_e32 v128, v128
	v_exp_f32_e32 v129, v129
	v_exp_f32_e32 v130, v130
	v_exp_f32_e32 v131, v131
	v_pk_add_f32 v[124:125], v[124:125], s[100:101]
	v_pk_add_f32 v[126:127], v[126:127], s[100:101]
	v_pk_add_f32 v[128:129], v[128:129], s[100:101]
	v_pk_add_f32 v[130:131], v[130:131], s[100:101]
	ds_read_b128 v[236:239], v187 offset:7184
	ds_read_b128 v[120:123], v187 offset:5136
	v_rcp_f32_e32 v124, v124
	v_rcp_f32_e32 v125, v125
	v_rcp_f32_e32 v126, v126
	ds_read_b128 v[248:251], v187 offset:5648
	v_rcp_f32_e32 v127, v127
	v_rcp_f32_e32 v128, v128
	v_rcp_f32_e32 v129, v129
	v_rcp_f32_e32 v130, v130
	ds_read_b128 v[132:135], v187 offset:6160
	v_rcp_f32_e32 v131, v131
	v_mul_f32_e32 v139, v178, v124
	v_mul_f32_e32 v170, v179, v125
	v_pk_mul_f32 v[240:241], v[180:181], v[126:127]
	v_pk_mul_f32 v[242:243], v[230:231], v[128:129]
	ds_read_b128 v[232:235], v187 offset:6672
	v_pk_mul_f32 v[252:253], v[246:247], v[130:131]
	v_lshlrev_b32_e32 v96, 16, v46
	v_and_b32_e32 v97, 0xffff0000, v46
	v_lshlrev_b32_e32 v144, 16, v47
	v_and_b32_e32 v145, 0xffff0000, v47
	s_waitcnt lgkmcnt(3)
	v_pk_fma_f32 v[178:179], v[120:121], v[96:97], v[236:237]
	v_pk_fma_f32 v[180:181], v[122:123], v[144:145], v[238:239]
	v_lshlrev_b32_e32 v96, 16, v50
	v_and_b32_e32 v97, 0xffff0000, v50
	v_lshlrev_b32_e32 v144, 16, v51
	v_and_b32_e32 v145, 0xffff0000, v51
	s_waitcnt lgkmcnt(2)
	v_pk_fma_f32 v[178:179], v[248:249], v[96:97], v[178:179]
	v_pk_fma_f32 v[180:181], v[250:251], v[144:145], v[180:181]
	v_pk_fma_f32 v[230:231], v[120:121], v[96:97], v[236:237]
	v_pk_fma_f32 v[246:247], v[122:123], v[144:145], v[238:239]
	v_lshlrev_b32_e32 v96, 16, v54
	v_and_b32_e32 v97, 0xffff0000, v54
	v_lshlrev_b32_e32 v144, 16, v55
	v_and_b32_e32 v145, 0xffff0000, v55
	s_waitcnt lgkmcnt(1)
	v_pk_fma_f32 v[178:179], v[132:133], v[96:97], v[178:179]
	v_pk_fma_f32 v[180:181], v[134:135], v[144:145], v[180:181]
	v_pk_fma_f32 v[230:231], v[248:249], v[96:97], v[230:231]
	v_pk_fma_f32 v[246:247], v[250:251], v[144:145], v[246:247]
	v_lshlrev_b32_e32 v96, 16, v58
	v_and_b32_e32 v97, 0xffff0000, v58
	v_lshlrev_b32_e32 v144, 16, v59
	v_and_b32_e32 v145, 0xffff0000, v59
	s_waitcnt lgkmcnt(0)
	v_pk_fma_f32 v[178:179], v[232:233], v[96:97], v[178:179]
	v_pk_fma_f32 v[180:181], v[234:235], v[144:145], v[180:181]
	v_pk_fma_f32 v[230:231], v[132:133], v[96:97], v[230:231]
	v_pk_fma_f32 v[246:247], v[134:135], v[144:145], v[246:247]
	v_lshlrev_b32_e32 v96, 16, v62
	v_and_b32_e32 v97, 0xffff0000, v62
	v_lshlrev_b32_e32 v144, 16, v63
	v_and_b32_e32 v145, 0xffff0000, v63
	v_pk_fma_f32 v[230:231], v[232:233], v[96:97], v[230:231]
	v_pk_fma_f32 v[246:247], v[234:235], v[144:145], v[246:247]
	v_pk_mul_f32 v[124:125], v[178:179], s[98:99]
	v_pk_mul_f32 v[126:127], v[180:181], s[98:99]
	v_pk_mul_f32 v[128:129], v[230:231], s[98:99]
	v_pk_mul_f32 v[130:131], v[246:247], s[98:99]
	v_exp_f32_e32 v124, v124
	v_exp_f32_e32 v125, v125
	v_exp_f32_e32 v126, v126
	v_exp_f32_e32 v127, v127
	v_exp_f32_e32 v128, v128
	v_exp_f32_e32 v129, v129
	v_exp_f32_e32 v130, v130
	v_exp_f32_e32 v131, v131
	v_pk_add_f32 v[124:125], v[124:125], s[100:101]
	v_pk_add_f32 v[126:127], v[126:127], s[100:101]
	v_pk_add_f32 v[128:129], v[128:129], s[100:101]
	v_pk_add_f32 v[130:131], v[130:131], s[100:101]
	v_rcp_f32_e32 v124, v124
	v_rcp_f32_e32 v125, v125
	v_rcp_f32_e32 v126, v126
	v_rcp_f32_e32 v127, v127
	v_rcp_f32_e32 v128, v128
	v_rcp_f32_e32 v129, v129
	v_rcp_f32_e32 v130, v130
	v_rcp_f32_e32 v131, v131
	v_mul_f32_e32 v122, v178, v124
	v_mul_f32_e32 v99, v179, v125
	v_pk_mul_f32 v[100:101], v[180:181], v[126:127]
	v_pk_mul_f32 v[118:119], v[230:231], v[128:129]
	v_pk_mul_f32 v[120:121], v[246:247], v[130:131]
	s_cmp_lg_u32 s83, 1
	v_readlane_b32 s66, v254, 6
	v_readlane_b32 s67, v254, 7
	v_cvt_pk_bf16_f32 v96, v139, v170
	v_cvt_pk_bf16_f32 v97, v240, v241
	v_cvt_pk_bf16_f32 v98, v122, v99
	v_cvt_pk_bf16_f32 v99, v100, v101
	v_cvt_pk_bf16_f32 v235, v104, v105
	v_cvt_pk_bf16_f32 v231, v102, v103
	s_cselect_b64 s[0:1], -1, 0
	s_cmp_eq_u32 s83, 1
	v_lshl_add_u64 v[104:105], s[66:67], 0, v[174:175]
	ds_write_b128 v207, v[96:99]
	v_cvt_pk_bf16_f32 v96, v242, v243
	v_cvt_pk_bf16_f32 v97, v252, v253
	v_cvt_pk_bf16_f32 v98, v118, v119
	v_cvt_pk_bf16_f32 v99, v120, v121
	ds_write_b128 v208, v[96:99]
	v_cvt_pk_bf16_f32 v233, v106, v107
	v_cvt_pk_bf16_f32 v236, v110, v111
	v_cvt_pk_bf16_f32 v234, v112, v113
	v_cvt_pk_bf16_f32 v229, v108, v109
	v_cvt_pk_bf16_f32 v232, v114, v115
	v_cvt_pk_bf16_f32 v230, v116, v117
	s_cbranch_scc1 .LBB0_468
	s_mov_b64 vcc, 0x64d5000
	v_lshl_add_u64 v[4:5], v[104:105], 0, vcc
	s_mov_b64 vcc, 0x64d8000
	v_lshl_add_u64 v[8:9], v[104:105], 0, vcc
	s_mov_b64 vcc, 0x64db000
	v_lshl_add_u64 v[12:13], v[104:105], 0, vcc
	global_load_dwordx4 v[4:7], v[4:5], off offset:3712
	s_nop 0
	global_load_dwordx4 v[8:11], v[8:9], off offset:3840
	s_mov_b64 vcc, 0x64df000
	v_lshl_add_u64 v[16:17], v[104:105], 0, vcc
	s_mov_b64 vcc, 0x64e2000
	v_lshl_add_u64 v[24:25], v[104:105], 0, vcc
	global_load_dwordx4 v[12:15], v[12:13], off offset:3968
	s_nop 0
	global_load_dwordx4 v[16:19], v[16:17], off
	global_load_dwordx4 v[24:27], v[24:25], off offset:128
